# baseline (speedup 1.0000x reference)
.LBB0_639:
	v_mov_b32_e32 v65, v64
	v_pk_add_f32 v[50:51], v[50:51], v[64:65] op_sel_hi:[1,0] neg_lo:[0,1] neg_hi:[0,1]
	v_pk_add_f32 v[114:115], v[116:117], v[64:65] op_sel_hi:[1,0] neg_lo:[0,1] neg_hi:[0,1]
	v_exp_f32_e32 v128, v50
	v_exp_f32_e32 v129, v51
	v_pk_add_f32 v[50:51], v[52:53], v[64:65] op_sel_hi:[1,0] neg_lo:[0,1] neg_hi:[0,1]
	v_exp_f32_e32 v114, v114
	v_exp_f32_e32 v116, v50
	v_exp_f32_e32 v117, v51
	v_pk_add_f32 v[50:51], v[54:55], v[64:65] op_sel_hi:[1,0] neg_lo:[0,1] neg_hi:[0,1]
	v_exp_f32_e32 v115, v115
	v_exp_f32_e32 v126, v50
	v_exp_f32_e32 v127, v51
	v_pk_add_f32 v[50:51], v[56:57], v[64:65] op_sel_hi:[1,0] neg_lo:[0,1] neg_hi:[0,1]
	v_pk_add_f32 v[160:161], v[34:35], v[64:65] neg_lo:[0,1] neg_hi:[0,1]
	v_exp_f32_e32 v118, v50
	v_exp_f32_e32 v119, v51
	v_pk_add_f32 v[50:51], v[58:59], v[64:65] op_sel_hi:[1,0] neg_lo:[0,1] neg_hi:[0,1]
	v_pk_add_f32 v[180:181], v[36:37], v[64:65] neg_lo:[0,1] neg_hi:[0,1]
	v_exp_f32_e32 v124, v50
	v_exp_f32_e32 v125, v51
	v_pk_add_f32 v[50:51], v[60:61], v[64:65] op_sel_hi:[1,0] neg_lo:[0,1] neg_hi:[0,1]
	v_pk_add_f32 v[182:183], v[38:39], v[64:65] neg_lo:[0,1] neg_hi:[0,1]
	v_exp_f32_e32 v120, v50
	v_exp_f32_e32 v121, v51
	v_pk_add_f32 v[50:51], v[62:63], v[64:65] op_sel_hi:[1,0] neg_lo:[0,1] neg_hi:[0,1]
	v_pk_add_f32 v[208:209], v[40:41], v[64:65] neg_lo:[0,1] neg_hi:[0,1]
	v_exp_f32_e32 v122, v50
	v_exp_f32_e32 v123, v51
	v_pk_add_f32 v[210:211], v[42:43], v[64:65] neg_lo:[0,1] neg_hi:[0,1]
	v_pk_add_f32 v[212:213], v[44:45], v[64:65] neg_lo:[0,1] neg_hi:[0,1]
	v_pk_add_f32 v[214:215], v[46:47], v[64:65] neg_lo:[0,1] neg_hi:[0,1]
	v_pk_add_f32 v[216:217], v[48:49], v[64:65] neg_lo:[0,1] neg_hi:[0,1]
	s_waitcnt lgkmcnt(0)
	s_barrier
	ds_read_b128 v[34:37], v166 offset:16384
	ds_read_b128 v[50:53], v166 offset:20480
	ds_read_b128 v[200:203], v169 offset:16384
	ds_read_b128 v[204:207], v169 offset:20480
	v_exp_f32_e32 v180, v180
	v_exp_f32_e32 v181, v181
	s_waitcnt lgkmcnt(0)
	v_mfma_f32_32x32x16_bf16 v[34:49], v[34:37], v[78:81], 0
	v_exp_f32_e32 v182, v182
	v_exp_f32_e32 v183, v183
	v_mfma_f32_32x32x16_bf16 v[50:65], v[50:53], v[78:81], 0
	v_mfma_f32_32x32x16_bf16 v[34:49], v[200:203], v[74:77], v[34:49]
	v_mfma_f32_32x32x16_bf16 v[50:65], v[204:207], v[74:77], v[50:65]
	ds_read_b128 v[200:203], v192 offset:16384
	ds_read_b128 v[204:207], v192 offset:20480
	s_waitcnt lgkmcnt(0)
	v_mfma_f32_32x32x16_bf16 v[34:49], v[200:203], v[70:73], v[34:49]
	v_mfma_f32_32x32x16_bf16 v[50:65], v[204:207], v[70:73], v[50:65]
	ds_read_b128 v[200:203], v191 offset:16384
	ds_read_b128 v[204:207], v191 offset:20480
	s_waitcnt lgkmcnt(0)
	v_mfma_f32_32x32x16_bf16 v[34:49], v[200:203], v[66:69], v[34:49]
	v_exp_f32_e32 v200, v160
	v_exp_f32_e32 v201, v161
	v_pk_add_f32 v[160:161], v[114:115], 0 op_sel_hi:[1,0]
	v_exp_f32_e32 v202, v208
	v_pk_add_f32 v[160:161], v[128:129], v[160:161]
	v_exp_f32_e32 v203, v209
	v_pk_add_f32 v[160:161], v[116:117], v[160:161]
	v_mfma_f32_32x32x16_bf16 v[50:65], v[204:207], v[66:69], v[50:65]
	v_add_f32_e64 v160, v126, v160
	v_add_f32_e64 v161, v127, v161
	v_exp_f32_e32 v204, v210
	v_pk_add_f32 v[160:161], v[118:119], v[160:161]
	v_exp_f32_e32 v205, v211
	v_pk_add_f32 v[160:161], v[124:125], v[160:161]
	v_exp_f32_e32 v206, v212
	v_pk_add_f32 v[160:161], v[120:121], v[160:161]
	v_exp_f32_e32 v207, v213
	v_pk_add_f32 v[160:161], v[122:123], v[160:161]
	v_exp_f32_e32 v208, v214
	v_pk_add_f32 v[160:161], v[200:201], v[160:161]
	v_exp_f32_e32 v209, v215
	v_pk_add_f32 v[160:161], v[180:181], v[160:161]
	v_exp_f32_e32 v210, v216
	v_pk_add_f32 v[160:161], v[182:183], v[160:161]
	v_exp_f32_e32 v211, v217
	v_pk_add_f32 v[160:161], v[202:203], v[160:161]
	v_cvt_pk_bf16_f32 v114, v114, v115
	v_cvt_pk_bf16_f32 v115, v128, v129
	v_cvt_pk_bf16_f32 v116, v116, v117
	v_cvt_pk_bf16_f32 v117, v126, v127
	v_cvt_pk_bf16_f32 v118, v118, v119
	s_nop 0
	v_pk_add_f32 v[160:161], v[204:205], v[160:161]
	v_cvt_pk_bf16_f32 v119, v124, v125
	v_cvt_pk_bf16_f32 v120, v120, v121
	v_cvt_pk_bf16_f32 v121, v122, v123
	v_cvt_pk_bf16_f32 v122, v200, v201
	v_cvt_pk_bf16_f32 v123, v180, v181
	s_nop 0
	v_pk_add_f32 v[160:161], v[206:207], v[160:161]
	v_cvt_pk_bf16_f32 v124, v182, v183
	v_cvt_pk_bf16_f32 v125, v202, v203
	v_cvt_pk_bf16_f32 v126, v204, v205
	v_cvt_pk_bf16_f32 v127, v206, v207
	v_cvt_pk_bf16_f32 v128, v208, v209
	s_nop 0
	v_pk_add_f32 v[160:161], v[208:209], v[160:161]
	v_cvt_pk_bf16_f32 v129, v210, v211
	v_permlane32_swap_b32_e32 v114, v116
	v_pk_add_f32 v[160:161], v[210:211], v[160:161]
	v_permlane32_swap_b32_e32 v115, v117
	v_pk_add_f32 v[160:161], v[160:161], v[160:161] op_sel:[0,1] op_sel_hi:[1,0]
	v_permlane32_swap_b32_e32 v118, v120
	v_mov_b32_e32 v161, v160
	s_nop 1
	v_permlane32_swap_b32_e32 v160, v161
	v_permlane32_swap_b32_e32 v119, v121
	v_permlane32_swap_b32_e32 v122, v124
	v_permlane32_swap_b32_e32 v123, v125
	v_permlane32_swap_b32_e32 v126, v128
	v_permlane32_swap_b32_e32 v127, v129
	v_cmp_lt_i32_e32 vcc, s30, v193
	v_cmp_ge_i32_e64 s[14:15], s30, v193
	s_and_saveexec_b64 s[8:9], vcc
	s_cbranch_execnz .Lrefill_1
	s_waitcnt vmcnt(0)
	s_branch .LBB0_641
.Lrefill_1:
	v_subrev_u32_e32 v82, 32, v196
	v_mad_i64_i32 v[82:83], s[4:5], v82, s86, 0
	v_or_b32_e32 v82, v82, v141
	v_lshl_add_u64 v[86:87], v[82:83], 1, v[144:145]
	v_mad_i64_i32 v[82:83], s[4:5], v196, s86, 0
	v_or_b32_e32 v82, v82, v141
	v_lshl_add_u64 v[94:95], v[82:83], 1, v[144:145]
	flat_load_dwordx4 v[82:85], v[86:87] offset:1024
	s_nop 0
	flat_load_dwordx4 v[86:89], v[86:87] offset:512
	s_nop 0
	flat_load_dwordx4 v[90:93], v[94:95] offset:1024
	s_nop 0
	flat_load_dwordx4 v[94:97], v[94:95] offset:512

.LBB0_644:
	s_barrier
	s_waitcnt vmcnt(4)
	v_cmp_gt_f32_e32 vcc, 1.0, v65
	ds_write_b128 v157, v[98:101] offset:8192
	ds_write_b128 v164, v[110:113] offset:8192
	ds_write_b128 v167, v[102:105] offset:24576
	ds_write_b128 v168, v[106:109] offset:24576
	s_cbranch_vccz .LBB0_631
	s_and_saveexec_b64 s[4:5], s[12:13]
	s_cbranch_execz .LBB0_630
	ds_write_b32 v155, v65 offset:32896
	s_branch .LBB0_630

.LBB0_679:
	v_mov_b32_e32 v117, v116
	v_pk_add_f32 v[50:51], v[50:51], v[116:117] op_sel_hi:[1,0] neg_lo:[0,1] neg_hi:[0,1]
	v_pk_add_f32 v[158:159], v[34:35], v[116:117] neg_lo:[0,1] neg_hi:[0,1]
	v_exp_f32_e32 v114, v50
	v_exp_f32_e32 v115, v51
	v_pk_add_f32 v[50:51], v[52:53], v[116:117] op_sel_hi:[1,0] neg_lo:[0,1] neg_hi:[0,1]
	v_pk_add_f32 v[180:181], v[36:37], v[116:117] neg_lo:[0,1] neg_hi:[0,1]
	v_exp_f32_e32 v124, v50
	v_exp_f32_e32 v125, v51
	v_pk_add_f32 v[50:51], v[54:55], v[116:117] op_sel_hi:[1,0] neg_lo:[0,1] neg_hi:[0,1]
	v_pk_add_f32 v[182:183], v[38:39], v[116:117] neg_lo:[0,1] neg_hi:[0,1]
	v_exp_f32_e32 v128, v50
	v_exp_f32_e32 v129, v51
	v_pk_add_f32 v[50:51], v[56:57], v[116:117] op_sel_hi:[1,0] neg_lo:[0,1] neg_hi:[0,1]
	v_pk_add_f32 v[206:207], v[40:41], v[116:117] neg_lo:[0,1] neg_hi:[0,1]
	v_exp_f32_e32 v160, v50
	v_exp_f32_e32 v161, v51
	v_pk_add_f32 v[50:51], v[58:59], v[116:117] op_sel_hi:[1,0] neg_lo:[0,1] neg_hi:[0,1]
	v_pk_add_f32 v[208:209], v[42:43], v[116:117] neg_lo:[0,1] neg_hi:[0,1]
	v_exp_f32_e32 v118, v50
	v_exp_f32_e32 v119, v51
	v_pk_add_f32 v[50:51], v[60:61], v[116:117] op_sel_hi:[1,0] neg_lo:[0,1] neg_hi:[0,1]
	v_pk_add_f32 v[210:211], v[44:45], v[116:117] neg_lo:[0,1] neg_hi:[0,1]
	v_exp_f32_e32 v120, v50
	v_exp_f32_e32 v121, v51
	v_pk_add_f32 v[50:51], v[62:63], v[116:117] op_sel_hi:[1,0] neg_lo:[0,1] neg_hi:[0,1]
	v_pk_add_f32 v[212:213], v[46:47], v[116:117] neg_lo:[0,1] neg_hi:[0,1]
	v_exp_f32_e32 v126, v50
	v_exp_f32_e32 v127, v51
	v_pk_add_f32 v[50:51], v[64:65], v[116:117] op_sel_hi:[1,0] neg_lo:[0,1] neg_hi:[0,1]
	v_pk_add_f32 v[116:117], v[48:49], v[116:117] neg_lo:[0,1] neg_hi:[0,1]
	v_exp_f32_e32 v122, v50
	v_exp_f32_e32 v123, v51
	s_waitcnt lgkmcnt(0)
	s_barrier
	ds_read_b128 v[34:37], v169 offset:16384
	ds_read_b128 v[38:41], v169 offset:20480
	ds_read_b128 v[198:201], v168 offset:16384
	ds_read_b128 v[202:205], v168 offset:20480
	v_exp_f32_e32 v180, v180
	v_exp_f32_e32 v181, v181
	s_waitcnt lgkmcnt(0)
	v_mfma_f32_32x32x16_bf16 v[50:65], v[34:37], v[78:81], 0
	v_exp_f32_e32 v182, v182
	v_exp_f32_e32 v183, v183
	v_mfma_f32_32x32x16_bf16 v[34:49], v[38:41], v[78:81], 0
	v_mfma_f32_32x32x16_bf16 v[34:49], v[202:205], v[66:69], v[34:49]
	v_mfma_f32_32x32x16_bf16 v[50:65], v[198:201], v[66:69], v[50:65]
	ds_read_b128 v[198:201], v166 offset:16384
	ds_read_b128 v[202:205], v166 offset:20480
	s_waitcnt lgkmcnt(0)
	v_mfma_f32_32x32x16_bf16 v[34:49], v[202:205], v[70:73], v[34:49]
	v_mfma_f32_32x32x16_bf16 v[50:65], v[198:201], v[70:73], v[50:65]
	ds_read_b128 v[198:201], v191 offset:16384
	ds_read_b128 v[202:205], v191 offset:20480
	s_waitcnt lgkmcnt(0)
	v_mfma_f32_32x32x16_bf16 v[34:49], v[202:205], v[74:77], v[34:49]
	v_exp_f32_e32 v202, v208
	v_exp_f32_e32 v203, v209
	v_exp_f32_e32 v208, v116
	v_exp_f32_e32 v209, v117
	v_pk_add_f32 v[116:117], v[114:115], 0 op_sel_hi:[1,0]
	v_exp_f32_e32 v204, v210
	v_pk_add_f32 v[116:117], v[124:125], v[116:117]
	v_mfma_f32_32x32x16_bf16 v[50:65], v[198:201], v[74:77], v[50:65]
	v_add_f32_e64 v116, v128, v116
	v_add_f32_e64 v117, v129, v117
	v_exp_f32_e32 v198, v158
	v_pk_add_f32 v[116:117], v[160:161], v[116:117]
	v_exp_f32_e32 v199, v159
	v_pk_add_f32 v[116:117], v[118:119], v[116:117]
	v_exp_f32_e32 v200, v206
	v_pk_add_f32 v[116:117], v[120:121], v[116:117]
	v_exp_f32_e32 v201, v207
	v_pk_add_f32 v[116:117], v[126:127], v[116:117]
	v_exp_f32_e32 v205, v211
	v_pk_add_f32 v[116:117], v[122:123], v[116:117]
	v_exp_f32_e32 v206, v212
	v_pk_add_f32 v[116:117], v[198:199], v[116:117]
	v_exp_f32_e32 v207, v213
	v_pk_add_f32 v[116:117], v[180:181], v[116:117]
	v_cvt_pk_bf16_f32 v114, v114, v115
	v_cvt_pk_bf16_f32 v115, v124, v125
	v_cvt_pk_bf16_f32 v118, v118, v119
	v_cvt_pk_bf16_f32 v119, v120, v121
	v_cvt_pk_bf16_f32 v120, v126, v127
	s_nop 0
	v_pk_add_f32 v[116:117], v[182:183], v[116:117]
	v_cvt_pk_bf16_f32 v121, v122, v123
	v_cvt_pk_bf16_f32 v122, v198, v199
	v_cvt_pk_bf16_f32 v123, v180, v181
	v_cvt_pk_bf16_f32 v124, v182, v183
	v_cvt_pk_bf16_f32 v125, v200, v201
	s_nop 0
	v_pk_add_f32 v[116:117], v[200:201], v[116:117]
	v_cvt_pk_bf16_f32 v126, v202, v203
	v_cvt_pk_bf16_f32 v127, v204, v205
	v_permlane32_swap_b32_e32 v118, v120
	v_pk_add_f32 v[116:117], v[202:203], v[116:117]
	v_permlane32_swap_b32_e32 v119, v121
	v_pk_add_f32 v[116:117], v[204:205], v[116:117]
	v_permlane32_swap_b32_e32 v122, v124
	v_pk_add_f32 v[116:117], v[206:207], v[116:117]
	v_permlane32_swap_b32_e32 v123, v125
	v_pk_add_f32 v[116:117], v[208:209], v[116:117]
	s_nop 0
	v_pk_add_f32 v[158:159], v[116:117], v[116:117] op_sel:[0,1] op_sel_hi:[1,0]
	v_cvt_pk_bf16_f32 v116, v128, v129
	v_cvt_pk_bf16_f32 v117, v160, v161
	v_cvt_pk_bf16_f32 v128, v206, v207
	v_cvt_pk_bf16_f32 v129, v208, v209
	s_nop 0
	v_mov_b32_e32 v159, v158
	s_nop 1
	v_permlane32_swap_b32_e32 v158, v159
	v_permlane32_swap_b32_e32 v114, v116
	v_permlane32_swap_b32_e32 v115, v117
	v_permlane32_swap_b32_e32 v126, v128
	v_permlane32_swap_b32_e32 v127, v129
	v_cmp_lt_u32_e32 vcc, s30, v157
	s_and_saveexec_b64 s[22:23], vcc
	s_cbranch_execnz .Lrefill_0
	s_waitcnt vmcnt(0)
	s_branch .LBB0_681
.Lrefill_0:
	v_add_co_u32_e32 v82, vcc, 0xfffd8000, v142
	s_nop 1
	v_addc_co_u32_e32 v83, vcc, -1, v143, vcc
	v_add_co_u32_e32 v84, vcc, 0xfffd7f00, v142
	s_nop 1
	v_addc_co_u32_e32 v85, vcc, -1, v143, vcc
	v_add_co_u32_e32 v90, vcc, 0xffffff00, v142
	flat_load_dwordx4 v[86:89], v[82:83]
	s_nop 0
	flat_load_dwordx4 v[82:85], v[84:85]
	v_addc_co_u32_e32 v91, vcc, -1, v143, vcc
	flat_load_dwordx4 v[94:97], v[142:143]
	s_nop 0
	flat_load_dwordx4 v[90:93], v[90:91]

.LBB0_684:
	s_waitcnt lgkmcnt(0)
	s_barrier
	s_waitcnt vmcnt(4)
	v_cmp_gt_f32_e32 vcc, 1.0, v145
	ds_write_b128 v163, v[98:101] offset:8192
	ds_write_b128 v164, v[110:113] offset:8192
	ds_write_b128 v165, v[102:105] offset:24576
	ds_write_b128 v167, v[106:109] offset:24576
	s_cbranch_vccz .LBB0_671
	s_and_saveexec_b64 s[4:5], s[12:13]
	s_cbranch_execz .LBB0_670
	ds_write_b32 v141, v145 offset:32896
	s_branch .LBB0_670
